# attention phase start: lambda dot products by one load round trip + wave butterfly instead of 8 dependent load rounds
# speedup vs baseline: 1.0005x; 1.0005x over previous
.LBB0_227:
	v_lshlrev_b32_e32 v4, 2, v2
	global_load_dword v5, v4, s[16:17]
	global_load_dword v6, v4, s[18:19]
	global_load_dword v7, v4, s[20:21]
	global_load_dword v8, v4, s[22:23]
	s_waitcnt vmcnt(0)
	v_mul_f32_e32 v0, v5, v6
	v_mul_f32_e32 v1, v7, v8
	v_xor_b32_e32 v9, 4, v4
	ds_bpermute_b32 v10, v9, v0
	ds_bpermute_b32 v11, v9, v1
	s_waitcnt lgkmcnt(0)
	v_add_f32_e32 v0, v0, v10
	v_add_f32_e32 v1, v1, v11
	v_xor_b32_e32 v9, 8, v4
	ds_bpermute_b32 v10, v9, v0
	ds_bpermute_b32 v11, v9, v1
	s_waitcnt lgkmcnt(0)
	v_add_f32_e32 v0, v0, v10
	v_add_f32_e32 v1, v1, v11
	v_xor_b32_e32 v9, 16, v4
	ds_bpermute_b32 v10, v9, v0
	ds_bpermute_b32 v11, v9, v1
	s_waitcnt lgkmcnt(0)
	v_add_f32_e32 v0, v0, v10
	v_add_f32_e32 v1, v1, v11
	v_xor_b32_e32 v9, 32, v4
	ds_bpermute_b32 v10, v9, v0
	ds_bpermute_b32 v11, v9, v1
	s_waitcnt lgkmcnt(0)
	v_add_f32_e32 v0, v0, v10
	v_add_f32_e32 v1, v1, v11
	v_xor_b32_e32 v9, 64, v4
	ds_bpermute_b32 v10, v9, v0
	ds_bpermute_b32 v11, v9, v1
	s_waitcnt lgkmcnt(0)
	v_add_f32_e32 v0, v0, v10
	v_add_f32_e32 v1, v1, v11
	v_xor_b32_e32 v9, 128, v4
	ds_bpermute_b32 v10, v9, v0
	ds_bpermute_b32 v11, v9, v1
	s_waitcnt lgkmcnt(0)
	v_add_f32_e32 v0, v0, v10
	v_add_f32_e32 v1, v1, v11
	v_readlane_b32 s15, v255, 0
	v_readlane_b32 s0, v255, 1
	s_lshr_b32 s1, s15, 7
	s_bfe_u32 s16, s15, 0x10006
	v_add_u32_e32 v3, s0, v2
	s_lshl_b32 s0, s1, 14
	s_add_i32 s4, s0, 0
	s_add_u32 s42, s34, 0x20000
	s_addc_u32 s43, s35, 0
	s_lshl_b32 s5, s1, 5
	s_lshl_b32 s0, s16, 6
	v_and_b32_e32 v9, 63, v2
	v_writelane_b32 v255, s1, 30
	s_cmpk_lt_u32 s15, 0x80
	v_writelane_b32 v255, s0, 31
	s_cselect_b64 s[48:49], -1, 0
	s_add_i32 s0, 0, 0x1bc00
	v_lshlrev_b32_e32 v96, 3, v9
	v_lshlrev_b32_e32 v5, 1, v2
	v_lshrrev_b32_e32 v4, 1, v2
	v_add_u32_e32 v12, s0, v96
	v_readlane_b32 s0, v255, 2
	v_and_b32_e32 v6, 8, v5
	v_and_b32_e32 v4, 4, v4
	v_and_b32_e32 v11, 19, v2
	s_lshl_b32 s12, s0, 9
	s_add_i32 s0, 0, 0x11c00
	s_add_i32 s13, 0, 0x1c040
	v_or3_b32 v11, v6, v11, v4
	v_and_b32_e32 v6, 15, v2
	s_cmpk_gt_u32 s15, 0xff
	v_lshrrev_b32_e32 v7, 2, v2
	v_and_b32_e32 v8, 31, v2
	v_bfe_u32 v10, v2, 5, 1
	v_lshlrev_b32_e32 v4, 3, v6
	v_lshlrev_b32_e32 v6, 4, v6
	s_cselect_b64 s[50:51], -1, 0
	s_cmpk_lt_u32 s15, 0x100
	v_lshlrev_b32_e32 v2, 3, v2
	v_cmp_gt_u32_e64 s[18:19], 2, v9
	v_mul_f32_e32 v0, 0x3fb8aa3b, v0
	v_mul_f32_e32 v1, 0x3fb8aa3b, v1
	v_ashrrev_i32_e32 v140, 4, v3
	v_add_u32_e32 v13, s0, v6
	s_cselect_b64 s[28:29], -1, 0
	s_movk_i32 s0, 0x110
	v_and_b32_e32 v2, 24, v2
	v_writelane_b32 v255, s18, 32
	v_exp_f32_e32 v0, v0
	v_exp_f32_e32 v1, v1
	v_and_or_b32 v189, v5, 32, v2
	v_mul_lo_u32 v5, v140, s0
	s_and_b64 s[0:1], s[28:29], exec
	v_writelane_b32 v255, s19, 33
	v_cmp_gt_u32_e64 s[18:19], 4, v9
	s_cselect_b32 s0, 0, 32
	s_and_b32 s1, 64, s15
	v_writelane_b32 v255, s18, 34
	s_cmp_eq_u32 s16, 0
	s_cselect_b64 s[52:53], -1, 0
	v_writelane_b32 v255, s19, 35
	v_cmp_gt_u32_e64 s[18:19], 8, v9
	s_cmp_lg_u32 s1, 0
	v_sub_f32_e32 v0, v0, v1
	v_writelane_b32 v255, s18, 36
	v_add_u32_e32 v187, 0, v6
	v_cvt_f32_ubyte0_e32 v14, v11
	s_cselect_b64 s[66:67], -1, 0
	v_writelane_b32 v255, s19, 37
	v_cmp_gt_u32_e64 s[18:19], 16, v9
	s_add_u32 s27, s62, 0x10000000
	v_add_f32_e32 v147, 0x3e4ccccd, v0
	v_lshlrev_b32_e32 v0, 3, v10
	v_cvt_pk_bf16_f32 v14, v14, v14
	v_cmp_gt_u32_e64 s[10:11], 32, v9
	v_writelane_b32 v255, s18, 38
	s_addc_u32 s76, s63, 0
	s_add_i32 s77, s13, s0
	s_lshl_b32 s0, s89, 2
	v_add_u32_e32 v146, v187, v5
	v_mov_b32_e32 v97, 0
	v_cndmask_b32_e64 v100, 0, v14, s[10:11]
	v_mul_u32_u24_e32 v14, 0x110, v11
	v_or_b32_e32 v11, 32, v11
	v_and_or_b32 v7, v7, 3, v0
	s_movk_i32 s14, 0x140
	v_writelane_b32 v255, s19, 39
	s_add_i32 s77, s77, s0
	v_mad_u64_u32 v[148:149], s[0:1], v140, 48, v[146:147]
	v_lshlrev_b32_e32 v1, 2, v8
	v_lshlrev_b32_e32 v6, 4, v10
	v_cvt_f32_ubyte0_e32 v11, v11
	v_lshlrev_b32_e32 v2, 9, v10
	v_mad_u32_u24 v192, v7, s14, 0
	v_mov_b32_e32 v7, v97
	v_writelane_b32 v255, s16, 40
	s_lshl_b32 s0, s16, 9
	v_cmp_eq_u32_e64 s[22:23], 0, v3
	v_or_b32_e32 v186, s5, v8
	v_cmp_gt_i32_e64 s[8:9], 4, v3
	v_lshl_add_u32 v188, v3, 2, s13
	v_lshl_or_b32 v3, s16, 7, v6
	v_cvt_pk_bf16_f32 v11, v11, v11
	v_mul_lo_u32 v190, v140, s14
	v_add3_u32 v191, s4, v1, v2
	v_lshlrev_b32_e32 v2, 2, v10
	v_lshl_add_u64 v[144:145], s[24:25], 0, v[6:7]
	s_add_i32 s78, s0, 0
	v_sub_u32_e32 v1, v0, v8
	v_readlane_b32 s0, v255, 24
	s_mov_b32 s24, 1.0
	s_mov_b32 s41, 0
	v_ashrrev_i32_e32 v141, 31, v140
	v_cmp_eq_u32_e64 s[6:7], 0, v9
	v_mov_b32_e32 v101, v97
	v_mov_b32_e32 v102, v97
	v_mov_b32_e32 v103, v97
	v_cndmask_b32_e64 v104, 0, v11, s[10:11]
	v_mov_b32_e32 v105, v97
	v_mov_b32_e32 v106, v97
	v_mov_b32_e32 v107, v97
	v_lshl_add_u64 v[142:143], s[68:69], 0, v[96:97]
	v_add3_u32 v193, 0, v14, v3
	v_subrev_u32_e32 v149, 64, v186
	v_subrev_u32_e32 v194, s5, v1
	s_add_i32 s79, s0, -1
	s_add_i32 s72, 0, 0x1c000
	v_lshlrev_b32_e32 v150, 1, v0
	v_lshlrev_b32_e32 v152, 1, v4
	s_mov_b32 s80, 0xf800000
	v_mov_b32_e32 v195, 0x260
	v_add_u32_e32 v196, s12, v12
	v_add_u32_e32 v197, v13, v190
	s_mov_b32 s25, 0xc3200000
	v_lshlrev_b32_e32 v154, 1, v2
	v_mov_b32_e32 v198, 0x3727c5ac
	v_mbcnt_hi_u32_b32 v254, -1, v139
	v_mov_b32_e32 v199, 0x42800000
	s_mov_b32 s101, s2
	s_mov_b32 s100, 0
	s_and_b32 s101, s101, 7
	s_branch .LBB0_231
